# prologue x->bf16 row pass: eight row loads issued together
# speedup vs baseline: 1.0193x; 1.0081x over previous
; __device__ __forceinline__ u32x2 pack4(f32x4 v) { u32x2 r; r.x = cvt_pk_bf16(v[0], v[1]); r.y = cvt_pk_bf16(v[2], v[3]); return r; }
; __device__ __forceinline__ void pass_h2hb(const float* src, bf16_t* hb, float* ssq) {
;     ...
;     for (int row = GWAVE_ID; row < T_TOK; row += GWAVES) {
;         const f32x4* s = (const f32x4*)(src + (size_t)row * DM) + lane; u32x2* d = (u32x2*)(hb + (size_t)row * DM) + lane;
;         float acc = 0.f;
; #pragma unroll
;         for (int j = 0; j < 8; ++j) { const f32x4 v = s[64 * j]; acc += (v[0] * v[0] + v[1] * v[1]) + (v[2] * v[2] + v[3] * v[3]); d[64 * j] = pack4(v); }
;         acc = wave_sum(acc);
;         if (lane == 0) ssq[row] = acc;
;     }
.LBB0_728:
	s_waitcnt lgkmcnt(0)
	global_load_dwordx4 v[18:21], v[4:5], off offset:-4096
	global_load_dwordx4 v[120:123], v[4:5], off offset:-3072
	global_load_dwordx4 v[124:127], v[4:5], off offset:-2048
	global_load_dwordx4 v[128:131], v[4:5], off offset:-1024
	global_load_dwordx4 v[132:135], v[4:5], off
	global_load_dwordx4 v[136:139], v[4:5], off offset:1024
	global_load_dwordx4 v[140:143], v[4:5], off offset:2048
	global_load_dwordx4 v[144:147], v[4:5], off offset:3072
	v_lshl_add_u64 v[22:23], s[92:93], 0, v[6:7]
	s_mov_b32 s2, 0xfc00000
	v_add_co_u32_e32 v50, vcc, s2, v22
	s_waitcnt vmcnt(7)
	v_cvt_pk_bf16_f32 v22, v18, v19
	v_addc_co_u32_e32 v51, vcc, 0, v23, vcc
	v_cvt_pk_bf16_f32 v23, v20, v21
	global_store_dwordx2 v[50:51], v[22:23], off
	v_mul_f32_e32 v1, v19, v19
	v_mul_f32_e32 v19, v21, v21
	v_fmac_f32_e32 v1, v18, v18
	v_fmac_f32_e32 v19, v20, v20
	v_add_f32_e32 v1, v1, v19
	s_waitcnt vmcnt(7)
	v_mov_b64_e32 v[22:23], v[120:121]
	v_mov_b64_e32 v[24:25], v[122:123]
	v_cvt_pk_bf16_f32 v26, v22, v23
	v_cvt_pk_bf16_f32 v27, v24, v25
	global_store_dwordx2 v[50:51], v[26:27], off offset:512
	v_mul_f32_e32 v18, v23, v23
	v_mul_f32_e32 v19, v25, v25
	v_fmac_f32_e32 v18, v22, v22
	v_fmac_f32_e32 v19, v24, v24
	v_add_f32_e32 v18, v18, v19
	v_add_f32_e32 v1, v1, v18
	s_waitcnt vmcnt(7)
	v_mov_b64_e32 v[26:27], v[124:125]
	v_mov_b64_e32 v[28:29], v[126:127]
	v_cvt_pk_bf16_f32 v30, v26, v27
	v_cvt_pk_bf16_f32 v31, v28, v29
	global_store_dwordx2 v[50:51], v[30:31], off offset:1024
	v_mul_f32_e32 v18, v27, v27
	v_mul_f32_e32 v19, v29, v29
	v_fmac_f32_e32 v18, v26, v26
	v_fmac_f32_e32 v19, v28, v28
	v_add_f32_e32 v18, v18, v19
	v_add_f32_e32 v1, v1, v18
	s_waitcnt vmcnt(7)
	v_mov_b64_e32 v[30:31], v[128:129]
	v_mov_b64_e32 v[32:33], v[130:131]
	v_cvt_pk_bf16_f32 v34, v30, v31
	v_cvt_pk_bf16_f32 v35, v32, v33
	global_store_dwordx2 v[50:51], v[34:35], off offset:1536
	v_mul_f32_e32 v18, v31, v31
	v_mul_f32_e32 v19, v33, v33
	v_fmac_f32_e32 v18, v30, v30
	v_fmac_f32_e32 v19, v32, v32
	v_add_f32_e32 v18, v18, v19
	v_add_f32_e32 v1, v1, v18
	s_waitcnt vmcnt(7)
	v_mov_b64_e32 v[34:35], v[132:133]
	v_mov_b64_e32 v[36:37], v[134:135]
	v_cvt_pk_bf16_f32 v38, v34, v35
	v_cvt_pk_bf16_f32 v39, v36, v37
	global_store_dwordx2 v[50:51], v[38:39], off offset:2048
	v_mul_f32_e32 v18, v35, v35
	v_mul_f32_e32 v19, v37, v37
	v_fmac_f32_e32 v18, v34, v34
	v_fmac_f32_e32 v19, v36, v36
	v_add_f32_e32 v18, v18, v19
	v_add_f32_e32 v1, v1, v18
	s_waitcnt vmcnt(7)
	v_mov_b64_e32 v[38:39], v[136:137]
	v_mov_b64_e32 v[40:41], v[138:139]
	v_cvt_pk_bf16_f32 v42, v38, v39
	v_cvt_pk_bf16_f32 v43, v40, v41
	global_store_dwordx2 v[50:51], v[42:43], off offset:2560
	v_mul_f32_e32 v18, v39, v39
	v_mul_f32_e32 v19, v41, v41
	v_fmac_f32_e32 v18, v38, v38
	v_fmac_f32_e32 v19, v40, v40
	v_add_f32_e32 v18, v18, v19
	v_add_f32_e32 v1, v1, v18
	s_waitcnt vmcnt(7)
	v_mov_b64_e32 v[42:43], v[140:141]
	v_mov_b64_e32 v[44:45], v[142:143]
	v_cvt_pk_bf16_f32 v46, v42, v43
	v_cvt_pk_bf16_f32 v47, v44, v45
	global_store_dwordx2 v[50:51], v[46:47], off offset:3072
	v_mul_f32_e32 v18, v43, v43
	v_mul_f32_e32 v19, v45, v45
	v_fmac_f32_e32 v18, v42, v42
	v_fmac_f32_e32 v19, v44, v44
	v_add_f32_e32 v18, v18, v19
	v_add_f32_e32 v1, v1, v18
	s_waitcnt vmcnt(7)
	v_mov_b64_e32 v[46:47], v[144:145]
	v_mov_b64_e32 v[48:49], v[146:147]
	v_mul_f32_e32 v18, v47, v47
	v_mul_f32_e32 v19, v49, v49
	v_fmac_f32_e32 v18, v46, v46
	v_fmac_f32_e32 v19, v48, v48
	v_add_f32_e32 v18, v18, v19
	v_add_f32_e32 v1, v1, v18
	ds_bpermute_b32 v18, v12, v1
	v_cvt_pk_bf16_f32 v20, v46, v47
	v_cvt_pk_bf16_f32 v21, v48, v49
	global_store_dwordx2 v[50:51], v[20:21], off offset:3584
	s_waitcnt lgkmcnt(0)
	v_add_f32_e32 v1, v1, v18
	ds_bpermute_b32 v18, v13, v1
	s_waitcnt lgkmcnt(0)
	v_add_f32_e32 v1, v1, v18
	ds_bpermute_b32 v18, v14, v1
	s_waitcnt lgkmcnt(0)
	v_add_f32_e32 v1, v1, v18
	ds_bpermute_b32 v18, v15, v1
	s_waitcnt lgkmcnt(0)
	v_add_f32_e32 v1, v1, v18
	ds_bpermute_b32 v18, v16, v1
	s_waitcnt lgkmcnt(0)
	v_add_f32_e32 v1, v1, v18
	ds_bpermute_b32 v18, v17, v1
	s_and_saveexec_b64 s[10:11], s[0:1]
	s_cbranch_execz .LBB0_727
	v_lshl_add_u64 v[20:21], s[92:93], 0, v[2:3]
	s_waitcnt lgkmcnt(0)
	v_add_f32_e32 v1, v1, v18
	global_store_dword v[20:21], v1, off
	s_branch .LBB0_727
